# v7: v3 + attention phase-B gaps: 4 exps first, then 4 bfe, then 4 and (fresh temps v239-242) to break exp->and dependency stalls
# baseline (speedup 1.0000x reference)
.LBB0_2977:
	v_lshrrev_b32_e32 v62, v232, v208
	v_lshrrev_b32_e32 v63, v232, v209
	s_waitcnt lgkmcnt(14)
	v_mfma_f32_32x32x16_bf16 v[34:49], v[142:145], v[178:181], v[34:49]
	v_exp_f32_e32 v239, v98
	v_exp_f32_e32 v240, v99
	v_exp_f32_e32 v241, v100
	v_exp_f32_e32 v242, v101
	v_bfe_i32 v98, v62, 0, 1
	v_bfe_i32 v99, v62, 1, 1
	v_bfe_i32 v100, v62, 2, 1
	v_bfe_i32 v101, v62, 3, 1
	v_and_b32 v98, v98, v239
	v_and_b32 v99, v99, v240
	v_and_b32 v100, v100, v241
	v_and_b32 v101, v101, v242
	s_nop 0
	s_waitcnt lgkmcnt(12)
	v_mfma_f32_32x32x16_bf16 v[18:33], v[142:145], v[174:177], v[18:33]
	v_exp_f32_e32 v239, v102
	v_exp_f32_e32 v240, v103
	v_exp_f32_e32 v241, v104
	v_exp_f32_e32 v242, v105
	v_bfe_i32 v102, v62, 8, 1
	v_bfe_i32 v103, v62, 9, 1
	v_bfe_i32 v104, v62, 10, 1
	v_bfe_i32 v105, v62, 11, 1
	v_and_b32 v102, v102, v239
	v_and_b32 v103, v103, v240
	v_and_b32 v104, v104, v241
	v_and_b32 v105, v105, v242
	s_nop 0
	v_add_u32_e32 v64, s24, v235
	ds_read_b128 v[58:61], v64
	ds_read_b128 v[146:149], v64 offset:512
	s_waitcnt lgkmcnt(12)
	v_mfma_f32_32x32x16_bf16 v[34:49], v[138:141], v[166:169], v[34:49]
	v_exp_f32_e32 v239, v106
	v_exp_f32_e32 v240, v107
	v_exp_f32_e32 v241, v108
	v_exp_f32_e32 v242, v109
	v_bfe_i32 v106, v62, 16, 1
	v_bfe_i32 v107, v62, 17, 1
	v_bfe_i32 v108, v62, 18, 1
	v_bfe_i32 v109, v62, 19, 1
	v_and_b32 v106, v106, v239
	v_and_b32 v107, v107, v240
	v_and_b32 v108, v108, v241
	v_and_b32 v109, v109, v242
	s_nop 0
	ds_read_b128 v[174:177], v64 offset:2048
	ds_read_b128 v[162:165], v64 offset:2560
	s_waitcnt lgkmcnt(12)
	v_mfma_f32_32x32x16_bf16 v[18:33], v[138:141], v[74:77], v[18:33]
	v_exp_f32_e32 v239, v110
	v_exp_f32_e32 v240, v111
	v_exp_f32_e32 v241, v112
	v_exp_f32_e32 v242, v113
	v_bfe_i32 v110, v62, 24, 1
	v_bfe_i32 v111, v62, 25, 1
	v_bfe_i32 v112, v62, 26, 1
	v_bfe_i32 v113, v62, 27, 1
	v_and_b32 v110, v110, v239
	v_and_b32 v111, v111, v240
	v_and_b32 v112, v112, v241
	v_and_b32 v113, v113, v242
	s_nop 0
	ds_read_b128 v[178:181], v64 offset:4096
	ds_read_b128 v[166:169], v64 offset:4608
	s_waitcnt lgkmcnt(12)
	v_mfma_f32_32x32x16_bf16 v[34:49], v[134:137], v[70:73], v[34:49]
	v_exp_f32_e32 v239, v82
	v_exp_f32_e32 v240, v83
	v_exp_f32_e32 v241, v84
	v_exp_f32_e32 v242, v85
	v_bfe_i32 v82, v63, 0, 1
	v_bfe_i32 v83, v63, 1, 1
	v_bfe_i32 v84, v63, 2, 1
	v_bfe_i32 v85, v63, 3, 1
	v_and_b32 v82, v82, v239
	v_and_b32 v83, v83, v240
	v_and_b32 v84, v84, v241
	v_and_b32 v85, v85, v242
	s_nop 0
	ds_read_b128 v[182:185], v64 offset:6144
	ds_read_b128 v[170:173], v64 offset:6656
	s_waitcnt lgkmcnt(12)
	v_mfma_f32_32x32x16_bf16 v[18:33], v[134:137], v[66:69], v[18:33]
	v_exp_f32_e32 v239, v86
	v_exp_f32_e32 v240, v87
	v_exp_f32_e32 v241, v88
	v_exp_f32_e32 v242, v89
	v_bfe_i32 v86, v63, 8, 1
	v_bfe_i32 v87, v63, 9, 1
	v_bfe_i32 v88, v63, 10, 1
	v_bfe_i32 v89, v63, 11, 1
	v_and_b32 v86, v86, v239
	v_and_b32 v87, v87, v240
	v_and_b32 v88, v88, v241
	v_and_b32 v89, v89, v242
	s_nop 0
	s_waitcnt lgkmcnt(10)
	v_mfma_f32_32x32x16_bf16 v[34:49], v[122:125], v[54:57], v[34:49]
	v_exp_f32_e32 v239, v90
	v_exp_f32_e32 v240, v91
	v_exp_f32_e32 v241, v92
	v_exp_f32_e32 v242, v93
	v_bfe_i32 v90, v63, 16, 1
	v_bfe_i32 v91, v63, 17, 1
	v_bfe_i32 v92, v63, 18, 1
	v_bfe_i32 v93, v63, 19, 1
	v_and_b32 v90, v90, v239
	v_and_b32 v91, v91, v240
	v_and_b32 v92, v92, v241
	v_and_b32 v93, v93, v242
	s_nop 0
	s_waitcnt lgkmcnt(8)
	v_mfma_f32_32x32x16_bf16 v[18:33], v[122:125], v[50:53], v[18:33]
	v_exp_f32_e32 v239, v94
	v_exp_f32_e32 v240, v95
	v_exp_f32_e32 v241, v96
	v_exp_f32_e32 v242, v97
	v_bfe_i32 v94, v63, 24, 1
	v_bfe_i32 v95, v63, 25, 1
	v_bfe_i32 v96, v63, 26, 1
	v_bfe_i32 v97, v63, 27, 1
	v_and_b32 v94, v94, v239
	v_and_b32 v95, v95, v240
	v_and_b32 v96, v96, v241
	v_and_b32 v97, v97, v242
	s_nop 0
	v_lshl_add_u64 v[50:51], v[212:213], 0, -8
	global_load_dwordx2 v[208:209], v[50:51], off
	s_andn2_b64 vcc, exec, s[0:1]
	s_waitcnt vmcnt(3) lgkmcnt(0)
	s_barrier
	s_cbranch_vccnz .LBB0_2979
	s_waitcnt lgkmcnt(0)
	ds_read_b128 v[50:53], v231 offset:49248
	ds_read_b128 v[54:57], v231 offset:49216
	ds_read_b128 v[62:65], v231 offset:49184
	ds_read_b128 v[66:69], v231 offset:49152
	s_waitcnt lgkmcnt(3)
	v_pk_mul_f32 v[48:49], v[48:49], v[52:53]
	s_waitcnt lgkmcnt(2)
	v_pk_mul_f32 v[44:45], v[44:45], v[56:57]
	s_waitcnt lgkmcnt(1)
	v_pk_mul_f32 v[40:41], v[40:41], v[64:65]
	s_waitcnt lgkmcnt(0)
	v_pk_mul_f32 v[36:37], v[36:37], v[68:69]
	v_pk_mul_f32 v[46:47], v[46:47], v[50:51]
	v_pk_mul_f32 v[42:43], v[42:43], v[54:55]
	v_pk_mul_f32 v[38:39], v[38:39], v[62:63]
	v_pk_mul_f32 v[34:35], v[34:35], v[66:67]
	v_pk_mul_f32 v[32:33], v[32:33], v[52:53]
	v_pk_mul_f32 v[28:29], v[28:29], v[56:57]
	v_pk_mul_f32 v[24:25], v[24:25], v[64:65]
	v_pk_mul_f32 v[20:21], v[20:21], v[68:69]
	v_pk_mul_f32 v[30:31], v[30:31], v[50:51]
	v_pk_mul_f32 v[26:27], v[26:27], v[54:55]
	v_pk_mul_f32 v[22:23], v[22:23], v[62:63]
	v_pk_mul_f32 v[18:19], v[18:19], v[66:67]

.LBB0_2982:
	v_lshrrev_b32_e32 v90, v232, v206
	v_lshrrev_b32_e32 v91, v232, v207
	s_waitcnt lgkmcnt(14)
	v_mfma_f32_32x32x16_bf16 v[34:49], v[142:145], v[158:161], v[34:49]
	v_exp_f32_e32 v239, v66
	v_exp_f32_e32 v240, v67
	v_exp_f32_e32 v241, v68
	v_exp_f32_e32 v242, v69
	v_bfe_i32 v66, v90, 0, 1
	v_bfe_i32 v67, v90, 1, 1
	v_bfe_i32 v68, v90, 2, 1
	v_bfe_i32 v69, v90, 3, 1
	v_and_b32 v66, v66, v239
	v_and_b32 v67, v67, v240
	v_and_b32 v68, v68, v241
	v_and_b32 v69, v69, v242
	s_nop 0
	s_waitcnt lgkmcnt(12)
	v_mfma_f32_32x32x16_bf16 v[18:33], v[142:145], v[154:157], v[18:33]
	v_exp_f32_e32 v239, v70
	v_exp_f32_e32 v240, v71
	v_exp_f32_e32 v241, v72
	v_exp_f32_e32 v242, v73
	v_bfe_i32 v70, v90, 8, 1
	v_bfe_i32 v71, v90, 9, 1
	v_bfe_i32 v72, v90, 10, 1
	v_bfe_i32 v73, v90, 11, 1
	v_and_b32 v70, v70, v239
	v_and_b32 v71, v71, v240
	v_and_b32 v72, v72, v241
	v_and_b32 v73, v73, v242
	s_nop 0
	v_add_u32_e32 v92, s25, v235
	ds_read_b128 v[82:85], v92
	ds_read_b128 v[166:169], v92 offset:512
	s_waitcnt lgkmcnt(12)
	v_mfma_f32_32x32x16_bf16 v[34:49], v[138:141], v[150:153], v[34:49]
	v_exp_f32_e32 v239, v74
	v_exp_f32_e32 v240, v75
	v_exp_f32_e32 v241, v76
	v_exp_f32_e32 v242, v77
	v_bfe_i32 v74, v90, 16, 1
	v_bfe_i32 v75, v90, 17, 1
	v_bfe_i32 v76, v90, 18, 1
	v_bfe_i32 v77, v90, 19, 1
	v_and_b32 v74, v74, v239
	v_and_b32 v75, v75, v240
	v_and_b32 v76, v76, v241
	v_and_b32 v77, v77, v242
	s_nop 0
	ds_read_b128 v[170:173], v92 offset:2048
	ds_read_b128 v[158:161], v92 offset:2560
	s_waitcnt lgkmcnt(12)
	v_mfma_f32_32x32x16_bf16 v[18:33], v[138:141], v[146:149], v[18:33]
	v_exp_f32_e32 v239, v78
	v_exp_f32_e32 v240, v79
	v_exp_f32_e32 v241, v80
	v_exp_f32_e32 v242, v81
	v_bfe_i32 v78, v90, 24, 1
	v_bfe_i32 v79, v90, 25, 1
	v_bfe_i32 v80, v90, 26, 1
	v_bfe_i32 v81, v90, 27, 1
	v_and_b32 v78, v78, v239
	v_and_b32 v79, v79, v240
	v_and_b32 v80, v80, v241
	v_and_b32 v81, v81, v242
	s_nop 0
	ds_read_b128 v[162:165], v92 offset:4096
	ds_read_b128 v[150:153], v92 offset:4608
	s_waitcnt lgkmcnt(12)
	v_mfma_f32_32x32x16_bf16 v[34:49], v[134:137], v[106:109], v[34:49]
	v_exp_f32_e32 v239, v50
	v_exp_f32_e32 v240, v51
	v_exp_f32_e32 v241, v52
	v_exp_f32_e32 v242, v53
	v_bfe_i32 v50, v91, 0, 1
	v_bfe_i32 v51, v91, 1, 1
	v_bfe_i32 v52, v91, 2, 1
	v_bfe_i32 v53, v91, 3, 1
	v_and_b32 v50, v50, v239
	v_and_b32 v51, v51, v240
	v_and_b32 v52, v52, v241
	v_and_b32 v53, v53, v242
	s_nop 0
	ds_read_b128 v[154:157], v92 offset:6144
	ds_read_b128 v[146:149], v92 offset:6656
	s_waitcnt lgkmcnt(12)
	v_mfma_f32_32x32x16_bf16 v[18:33], v[134:137], v[102:105], v[18:33]
	v_exp_f32_e32 v239, v54
	v_exp_f32_e32 v240, v55
	v_exp_f32_e32 v241, v56
	v_exp_f32_e32 v242, v57
	v_bfe_i32 v54, v91, 8, 1
	v_bfe_i32 v55, v91, 9, 1
	v_bfe_i32 v56, v91, 10, 1
	v_bfe_i32 v57, v91, 11, 1
	v_and_b32 v54, v54, v239
	v_and_b32 v55, v55, v240
	v_and_b32 v56, v56, v241
	v_and_b32 v57, v57, v242
	s_nop 0
	s_waitcnt lgkmcnt(10)
	v_mfma_f32_32x32x16_bf16 v[34:49], v[122:125], v[98:101], v[34:49]
	v_exp_f32_e32 v239, v58
	v_exp_f32_e32 v240, v59
	v_exp_f32_e32 v241, v60
	v_exp_f32_e32 v242, v61
	v_bfe_i32 v58, v91, 16, 1
	v_bfe_i32 v59, v91, 17, 1
	v_bfe_i32 v60, v91, 18, 1
	v_bfe_i32 v61, v91, 19, 1
	v_and_b32 v58, v58, v239
	v_and_b32 v59, v59, v240
	v_and_b32 v60, v60, v241
	v_and_b32 v61, v61, v242
	s_nop 0
	s_waitcnt lgkmcnt(8)
	v_mfma_f32_32x32x16_bf16 v[18:33], v[122:125], v[86:89], v[18:33]
	v_exp_f32_e32 v239, v62
	v_exp_f32_e32 v240, v63
	v_exp_f32_e32 v241, v64
	v_exp_f32_e32 v242, v65
	v_bfe_i32 v62, v91, 24, 1
	v_bfe_i32 v63, v91, 25, 1
	v_bfe_i32 v64, v91, 26, 1
	v_bfe_i32 v65, v91, 27, 1
	v_and_b32 v62, v62, v239
	v_and_b32 v63, v63, v240
	v_and_b32 v64, v64, v241
	v_and_b32 v65, v65, v242
	s_nop 0
	global_load_dwordx2 v[206:207], v[212:213], off
	s_andn2_b64 vcc, exec, s[0:1]
	s_waitcnt vmcnt(3) lgkmcnt(0)
	s_barrier
	s_cbranch_vccnz .LBB0_2984
	s_waitcnt lgkmcnt(0)
	ds_read_b128 v[86:89], v231 offset:49248
	ds_read_b128 v[90:93], v231 offset:49216
	ds_read_b128 v[94:97], v231 offset:49184
	ds_read_b128 v[98:101], v231 offset:49152
	s_waitcnt lgkmcnt(3)
	v_pk_mul_f32 v[48:49], v[48:49], v[88:89]
	s_waitcnt lgkmcnt(2)
	v_pk_mul_f32 v[44:45], v[44:45], v[92:93]
	s_waitcnt lgkmcnt(1)
	v_pk_mul_f32 v[40:41], v[40:41], v[96:97]
	s_waitcnt lgkmcnt(0)
	v_pk_mul_f32 v[36:37], v[36:37], v[100:101]
	v_pk_mul_f32 v[46:47], v[46:47], v[86:87]
	v_pk_mul_f32 v[42:43], v[42:43], v[90:91]
	v_pk_mul_f32 v[38:39], v[38:39], v[94:95]
	v_pk_mul_f32 v[34:35], v[34:35], v[98:99]
	v_pk_mul_f32 v[32:33], v[32:33], v[88:89]
	v_pk_mul_f32 v[28:29], v[28:29], v[92:93]
	v_pk_mul_f32 v[24:25], v[24:25], v[96:97]
	v_pk_mul_f32 v[20:21], v[20:21], v[100:101]
	v_pk_mul_f32 v[30:31], v[30:31], v[86:87]
	v_pk_mul_f32 v[26:27], v[26:27], v[90:91]
	v_pk_mul_f32 v[22:23], v[22:23], v[94:95]
	v_pk_mul_f32 v[18:19], v[18:19], v[98:99]

.LBB0_2996:
	v_lshrrev_b32_e32 v62, v232, v208
	v_lshrrev_b32_e32 v63, v232, v209
	s_waitcnt lgkmcnt(14)
	v_mfma_f32_32x32x16_bf16 v[34:49], v[142:145], v[178:181], v[34:49]
	v_exp_f32_e32 v239, v98
	v_exp_f32_e32 v240, v99
	v_exp_f32_e32 v241, v100
	v_exp_f32_e32 v242, v101
	v_bfe_i32 v98, v62, 0, 1
	v_bfe_i32 v99, v62, 1, 1
	v_bfe_i32 v100, v62, 2, 1
	v_bfe_i32 v101, v62, 3, 1
	v_and_b32 v98, v98, v239
	v_and_b32 v99, v99, v240
	v_and_b32 v100, v100, v241
	v_and_b32 v101, v101, v242
	s_nop 0
	s_waitcnt lgkmcnt(12)
	v_mfma_f32_32x32x16_bf16 v[18:33], v[142:145], v[174:177], v[18:33]
	v_exp_f32_e32 v239, v102
	v_exp_f32_e32 v240, v103
	v_exp_f32_e32 v241, v104
	v_exp_f32_e32 v242, v105
	v_bfe_i32 v102, v62, 8, 1
	v_bfe_i32 v103, v62, 9, 1
	v_bfe_i32 v104, v62, 10, 1
	v_bfe_i32 v105, v62, 11, 1
	v_and_b32 v102, v102, v239
	v_and_b32 v103, v103, v240
	v_and_b32 v104, v104, v241
	v_and_b32 v105, v105, v242
	s_nop 0
	v_add_u32_e32 v64, s34, v235
	ds_read_b128 v[58:61], v64
	ds_read_b128 v[146:149], v64 offset:512
	s_waitcnt lgkmcnt(12)
	v_mfma_f32_32x32x16_bf16 v[34:49], v[138:141], v[166:169], v[34:49]
	v_exp_f32_e32 v239, v106
	v_exp_f32_e32 v240, v107
	v_exp_f32_e32 v241, v108
	v_exp_f32_e32 v242, v109
	v_bfe_i32 v106, v62, 16, 1
	v_bfe_i32 v107, v62, 17, 1
	v_bfe_i32 v108, v62, 18, 1
	v_bfe_i32 v109, v62, 19, 1
	v_and_b32 v106, v106, v239
	v_and_b32 v107, v107, v240
	v_and_b32 v108, v108, v241
	v_and_b32 v109, v109, v242
	s_nop 0
	ds_read_b128 v[170:173], v64 offset:2048
	ds_read_b128 v[158:161], v64 offset:2560
	s_waitcnt lgkmcnt(12)
	v_mfma_f32_32x32x16_bf16 v[18:33], v[138:141], v[74:77], v[18:33]
	v_exp_f32_e32 v239, v110
	v_exp_f32_e32 v240, v111
	v_exp_f32_e32 v241, v112
	v_exp_f32_e32 v242, v113
	v_bfe_i32 v110, v62, 24, 1
	v_bfe_i32 v111, v62, 25, 1
	v_bfe_i32 v112, v62, 26, 1
	v_bfe_i32 v113, v62, 27, 1
	v_and_b32 v110, v110, v239
	v_and_b32 v111, v111, v240
	v_and_b32 v112, v112, v241
	v_and_b32 v113, v113, v242
	s_nop 0
	ds_read_b128 v[174:177], v64 offset:4096
	ds_read_b128 v[162:165], v64 offset:4608
	s_waitcnt lgkmcnt(12)
	v_mfma_f32_32x32x16_bf16 v[34:49], v[134:137], v[70:73], v[34:49]
	v_exp_f32_e32 v239, v82
	v_exp_f32_e32 v240, v83
	v_exp_f32_e32 v241, v84
	v_exp_f32_e32 v242, v85
	v_bfe_i32 v82, v63, 0, 1
	v_bfe_i32 v83, v63, 1, 1
	v_bfe_i32 v84, v63, 2, 1
	v_bfe_i32 v85, v63, 3, 1
	v_and_b32 v82, v82, v239
	v_and_b32 v83, v83, v240
	v_and_b32 v84, v84, v241
	v_and_b32 v85, v85, v242
	s_nop 0
	ds_read_b128 v[178:181], v64 offset:6144
	ds_read_b128 v[166:169], v64 offset:6656
	s_waitcnt lgkmcnt(12)
	v_mfma_f32_32x32x16_bf16 v[18:33], v[134:137], v[66:69], v[18:33]
	v_exp_f32_e32 v239, v86
	v_exp_f32_e32 v240, v87
	v_exp_f32_e32 v241, v88
	v_exp_f32_e32 v242, v89
	v_bfe_i32 v86, v63, 8, 1
	v_bfe_i32 v87, v63, 9, 1
	v_bfe_i32 v88, v63, 10, 1
	v_bfe_i32 v89, v63, 11, 1
	v_and_b32 v86, v86, v239
	v_and_b32 v87, v87, v240
	v_and_b32 v88, v88, v241
	v_and_b32 v89, v89, v242
	s_nop 0
	s_waitcnt lgkmcnt(10)
	v_mfma_f32_32x32x16_bf16 v[34:49], v[122:125], v[54:57], v[34:49]
	v_exp_f32_e32 v239, v90
	v_exp_f32_e32 v240, v91
	v_exp_f32_e32 v241, v92
	v_exp_f32_e32 v242, v93
	v_bfe_i32 v90, v63, 16, 1
	v_bfe_i32 v91, v63, 17, 1
	v_bfe_i32 v92, v63, 18, 1
	v_bfe_i32 v93, v63, 19, 1
	v_and_b32 v90, v90, v239
	v_and_b32 v91, v91, v240
	v_and_b32 v92, v92, v241
	v_and_b32 v93, v93, v242
	s_nop 0
	s_waitcnt lgkmcnt(8)
	v_mfma_f32_32x32x16_bf16 v[18:33], v[122:125], v[50:53], v[18:33]
	v_exp_f32_e32 v239, v94
	v_exp_f32_e32 v240, v95
	v_exp_f32_e32 v241, v96
	v_exp_f32_e32 v242, v97
	v_bfe_i32 v94, v63, 24, 1
	v_bfe_i32 v95, v63, 25, 1
	v_bfe_i32 v96, v63, 26, 1
	v_bfe_i32 v97, v63, 27, 1
	v_and_b32 v94, v94, v239
	v_and_b32 v95, v95, v240
	v_and_b32 v96, v96, v241
	v_and_b32 v97, v97, v242
	s_nop 0
	s_lshr_b32 s68, s20, 3
	v_lshl_add_u64 v[50:51], v[204:205], 0, s[68:69]
	v_lshl_add_u64 v[50:51], v[50:51], 0, -8
	global_load_dwordx2 v[182:183], v[50:51], off
	s_andn2_b64 vcc, exec, s[0:1]
	s_waitcnt vmcnt(2) lgkmcnt(0)
	s_barrier
	s_cbranch_vccnz .LBB0_2998
	s_waitcnt lgkmcnt(0)
	ds_read_b128 v[50:53], v231 offset:49248
	ds_read_b128 v[54:57], v231 offset:49216
	ds_read_b128 v[62:65], v231 offset:49184
	ds_read_b128 v[66:69], v231 offset:49152
	s_waitcnt lgkmcnt(3)
	v_pk_mul_f32 v[48:49], v[48:49], v[52:53]
	s_waitcnt lgkmcnt(2)
	v_pk_mul_f32 v[44:45], v[44:45], v[56:57]
	s_waitcnt lgkmcnt(1)
	v_pk_mul_f32 v[40:41], v[40:41], v[64:65]
	s_waitcnt lgkmcnt(0)
	v_pk_mul_f32 v[36:37], v[36:37], v[68:69]
	v_pk_mul_f32 v[46:47], v[46:47], v[50:51]
	v_pk_mul_f32 v[42:43], v[42:43], v[54:55]
	v_pk_mul_f32 v[38:39], v[38:39], v[62:63]
	v_pk_mul_f32 v[34:35], v[34:35], v[66:67]
	v_pk_mul_f32 v[32:33], v[32:33], v[52:53]
	v_pk_mul_f32 v[28:29], v[28:29], v[56:57]
	v_pk_mul_f32 v[24:25], v[24:25], v[64:65]
	v_pk_mul_f32 v[20:21], v[20:21], v[68:69]
	v_pk_mul_f32 v[30:31], v[30:31], v[50:51]
	v_pk_mul_f32 v[26:27], v[26:27], v[54:55]
	v_pk_mul_f32 v[22:23], v[22:23], v[62:63]
	v_pk_mul_f32 v[18:19], v[18:19], v[66:67]

.LBB0_3001:
	v_lshrrev_b32_e32 v90, v232, v206
	v_lshrrev_b32_e32 v91, v232, v207
	s_waitcnt lgkmcnt(14)
	v_mfma_f32_32x32x16_bf16 v[34:49], v[142:145], v[154:157], v[34:49]
	v_exp_f32_e32 v239, v66
	v_exp_f32_e32 v240, v67
	v_exp_f32_e32 v241, v68
	v_exp_f32_e32 v242, v69
	v_bfe_i32 v66, v90, 0, 1
	v_bfe_i32 v67, v90, 1, 1
	v_bfe_i32 v68, v90, 2, 1
	v_bfe_i32 v69, v90, 3, 1
	v_and_b32 v66, v66, v239
	v_and_b32 v67, v67, v240
	v_and_b32 v68, v68, v241
	v_and_b32 v69, v69, v242
	s_nop 0
	s_waitcnt lgkmcnt(12)
	v_mfma_f32_32x32x16_bf16 v[18:33], v[142:145], v[150:153], v[18:33]
	v_exp_f32_e32 v239, v70
	v_exp_f32_e32 v240, v71
	v_exp_f32_e32 v241, v72
	v_exp_f32_e32 v242, v73
	v_bfe_i32 v70, v90, 8, 1
	v_bfe_i32 v71, v90, 9, 1
	v_bfe_i32 v72, v90, 10, 1
	v_bfe_i32 v73, v90, 11, 1
	v_and_b32 v70, v70, v239
	v_and_b32 v71, v71, v240
	v_and_b32 v72, v72, v241
	v_and_b32 v73, v73, v242
	s_nop 0
	v_add_u32_e32 v92, s20, v235
	ds_read_b128 v[158:161], v92
	ds_read_b128 v[150:153], v92 offset:512
	s_waitcnt lgkmcnt(12)
	v_mfma_f32_32x32x16_bf16 v[34:49], v[138:141], v[146:149], v[34:49]
	v_exp_f32_e32 v239, v74
	v_exp_f32_e32 v240, v75
	v_exp_f32_e32 v241, v76
	v_exp_f32_e32 v242, v77
	v_bfe_i32 v74, v90, 16, 1
	v_bfe_i32 v75, v90, 17, 1
	v_bfe_i32 v76, v90, 18, 1
	v_bfe_i32 v77, v90, 19, 1
	v_and_b32 v74, v74, v239
	v_and_b32 v75, v75, v240
	v_and_b32 v76, v76, v241
	v_and_b32 v77, v77, v242
	s_nop 0
	ds_read_b128 v[166:169], v92 offset:2048
	ds_read_b128 v[146:149], v92 offset:2560
	s_waitcnt lgkmcnt(12)
	v_mfma_f32_32x32x16_bf16 v[18:33], v[138:141], v[106:109], v[18:33]
	v_exp_f32_e32 v239, v78
	v_exp_f32_e32 v240, v79
	v_exp_f32_e32 v241, v80
	v_exp_f32_e32 v242, v81
	v_bfe_i32 v78, v90, 24, 1
	v_bfe_i32 v79, v90, 25, 1
	v_bfe_i32 v80, v90, 26, 1
	v_bfe_i32 v81, v90, 27, 1
	v_and_b32 v78, v78, v239
	v_and_b32 v79, v79, v240
	v_and_b32 v80, v80, v241
	v_and_b32 v81, v81, v242
	s_nop 0
	ds_read_b128 v[170:173], v92 offset:4096
	ds_read_b128 v[154:157], v92 offset:4608
	s_waitcnt lgkmcnt(12)
	v_mfma_f32_32x32x16_bf16 v[34:49], v[134:137], v[102:105], v[34:49]
	v_exp_f32_e32 v239, v50
	v_exp_f32_e32 v240, v51
	v_exp_f32_e32 v241, v52
	v_exp_f32_e32 v242, v53
	v_bfe_i32 v50, v91, 0, 1
	v_bfe_i32 v51, v91, 1, 1
	v_bfe_i32 v52, v91, 2, 1
	v_bfe_i32 v53, v91, 3, 1
	v_and_b32 v50, v50, v239
	v_and_b32 v51, v51, v240
	v_and_b32 v52, v52, v241
	v_and_b32 v53, v53, v242
	s_nop 0
	ds_read_b128 v[174:177], v92 offset:6144
	ds_read_b128 v[162:165], v92 offset:6656
	s_waitcnt lgkmcnt(12)
	v_mfma_f32_32x32x16_bf16 v[18:33], v[134:137], v[98:101], v[18:33]
	v_exp_f32_e32 v239, v54
	v_exp_f32_e32 v240, v55
	v_exp_f32_e32 v241, v56
	v_exp_f32_e32 v242, v57
	v_bfe_i32 v54, v91, 8, 1
	v_bfe_i32 v55, v91, 9, 1
	v_bfe_i32 v56, v91, 10, 1
	v_bfe_i32 v57, v91, 11, 1
	v_and_b32 v54, v54, v239
	v_and_b32 v55, v55, v240
	v_and_b32 v56, v56, v241
	v_and_b32 v57, v57, v242
	s_nop 0
	s_waitcnt lgkmcnt(10)
	v_mfma_f32_32x32x16_bf16 v[34:49], v[122:125], v[86:89], v[34:49]
	v_exp_f32_e32 v239, v58
	v_exp_f32_e32 v240, v59
	v_exp_f32_e32 v241, v60
	v_exp_f32_e32 v242, v61
	v_bfe_i32 v58, v91, 16, 1
	v_bfe_i32 v59, v91, 17, 1
	v_bfe_i32 v60, v91, 18, 1
	v_bfe_i32 v61, v91, 19, 1
	v_and_b32 v58, v58, v239
	v_and_b32 v59, v59, v240
	v_and_b32 v60, v60, v241
	v_and_b32 v61, v61, v242
	s_nop 0
	s_waitcnt lgkmcnt(8)
	v_mfma_f32_32x32x16_bf16 v[18:33], v[122:125], v[82:85], v[18:33]
	v_exp_f32_e32 v239, v62
	v_exp_f32_e32 v240, v63
	v_exp_f32_e32 v241, v64
	v_exp_f32_e32 v242, v65
	v_bfe_i32 v62, v91, 24, 1
	v_bfe_i32 v63, v91, 25, 1
	v_bfe_i32 v64, v91, 26, 1
	v_bfe_i32 v65, v91, 27, 1
	v_and_b32 v62, v62, v239
	v_and_b32 v63, v63, v240
	v_and_b32 v64, v64, v241
	v_and_b32 v65, v65, v242
	s_nop 0
	s_waitcnt vmcnt(0) lgkmcnt(0)
	s_barrier
	s_andn2_b64 vcc, exec, s[0:1]
	s_cbranch_vccnz .LBB0_3003
	s_waitcnt lgkmcnt(0)
	ds_read_b128 v[82:85], v231 offset:49248
	ds_read_b128 v[86:89], v231 offset:49216
	ds_read_b128 v[90:93], v231 offset:49184
	ds_read_b128 v[94:97], v231 offset:49152
	s_waitcnt lgkmcnt(3)
	v_pk_mul_f32 v[48:49], v[48:49], v[84:85]
	s_waitcnt lgkmcnt(2)
	v_pk_mul_f32 v[44:45], v[44:45], v[88:89]
	s_waitcnt lgkmcnt(1)
	v_pk_mul_f32 v[40:41], v[40:41], v[92:93]
	s_waitcnt lgkmcnt(0)
	v_pk_mul_f32 v[36:37], v[36:37], v[96:97]
	v_pk_mul_f32 v[46:47], v[46:47], v[82:83]
	v_pk_mul_f32 v[42:43], v[42:43], v[86:87]
	v_pk_mul_f32 v[38:39], v[38:39], v[90:91]
	v_pk_mul_f32 v[34:35], v[34:35], v[94:95]
	v_pk_mul_f32 v[32:33], v[32:33], v[84:85]
	v_pk_mul_f32 v[28:29], v[28:29], v[88:89]
	v_pk_mul_f32 v[24:25], v[24:25], v[92:93]
	v_pk_mul_f32 v[20:21], v[20:21], v[96:97]
	v_pk_mul_f32 v[30:31], v[30:31], v[82:83]
	v_pk_mul_f32 v[26:27], v[26:27], v[86:87]
	v_pk_mul_f32 v[22:23], v[22:23], v[90:91]
	v_pk_mul_f32 v[18:19], v[18:19], v[94:95]

.LBB0_3006:
	v_lshrrev_b32_e32 v50, v232, v182
	v_lshrrev_b32_e32 v51, v232, v183
	s_waitcnt lgkmcnt(14)
	v_mfma_f32_32x32x16_bf16 v[34:49], v[142:145], v[110:113], v[34:49]
	v_exp_f32_e32 v239, v82
	v_exp_f32_e32 v240, v83
	v_exp_f32_e32 v241, v84
	v_exp_f32_e32 v242, v85
	v_bfe_i32 v82, v50, 0, 1
	v_bfe_i32 v83, v50, 1, 1
	v_bfe_i32 v84, v50, 2, 1
	v_bfe_i32 v85, v50, 3, 1
	v_and_b32 v82, v82, v239
	v_and_b32 v83, v83, v240
	v_and_b32 v84, v84, v241
	v_and_b32 v85, v85, v242
	s_nop 0
	s_waitcnt lgkmcnt(12)
	v_mfma_f32_32x32x16_bf16 v[18:33], v[142:145], v[106:109], v[18:33]
	v_exp_f32_e32 v239, v86
	v_exp_f32_e32 v240, v87
	v_exp_f32_e32 v241, v88
	v_exp_f32_e32 v242, v89
	v_bfe_i32 v86, v50, 8, 1
	v_bfe_i32 v87, v50, 9, 1
	v_bfe_i32 v88, v50, 10, 1
	v_bfe_i32 v89, v50, 11, 1
	v_and_b32 v86, v86, v239
	v_and_b32 v87, v87, v240
	v_and_b32 v88, v88, v241
	v_and_b32 v89, v89, v242
	s_nop 0
	s_waitcnt lgkmcnt(10)
	v_mfma_f32_32x32x16_bf16 v[34:49], v[138:141], v[102:105], v[34:49]
	v_exp_f32_e32 v239, v90
	v_exp_f32_e32 v240, v91
	v_exp_f32_e32 v241, v92
	v_exp_f32_e32 v242, v93
	v_bfe_i32 v90, v50, 16, 1
	v_bfe_i32 v91, v50, 17, 1
	v_bfe_i32 v92, v50, 18, 1
	v_bfe_i32 v93, v50, 19, 1
	v_and_b32 v90, v90, v239
	v_and_b32 v91, v91, v240
	v_and_b32 v92, v92, v241
	v_and_b32 v93, v93, v242
	s_nop 0
	s_waitcnt lgkmcnt(8)
	v_mfma_f32_32x32x16_bf16 v[18:33], v[138:141], v[98:101], v[18:33]
	v_exp_f32_e32 v239, v94
	v_exp_f32_e32 v240, v95
	v_exp_f32_e32 v241, v96
	v_exp_f32_e32 v242, v97
	v_bfe_i32 v94, v50, 24, 1
	v_bfe_i32 v95, v50, 25, 1
	v_bfe_i32 v96, v50, 26, 1
	v_bfe_i32 v97, v50, 27, 1
	v_and_b32 v94, v94, v239
	v_and_b32 v95, v95, v240
	v_and_b32 v96, v96, v241
	v_and_b32 v97, v97, v242
	s_nop 0
	s_waitcnt lgkmcnt(6)
	v_mfma_f32_32x32x16_bf16 v[34:49], v[134:137], v[78:81], v[34:49]
	v_exp_f32_e32 v239, v2
	v_exp_f32_e32 v240, v3
	v_exp_f32_e32 v241, v4
	v_exp_f32_e32 v242, v5
	v_bfe_i32 v2, v51, 0, 1
	v_bfe_i32 v3, v51, 1, 1
	v_bfe_i32 v4, v51, 2, 1
	v_bfe_i32 v5, v51, 3, 1
	v_and_b32 v2, v2, v239
	v_and_b32 v3, v3, v240
	v_and_b32 v4, v4, v241
	v_and_b32 v5, v5, v242
	s_nop 0
	s_waitcnt lgkmcnt(4)
	v_mfma_f32_32x32x16_bf16 v[18:33], v[134:137], v[74:77], v[18:33]
	v_exp_f32_e32 v239, v6
	v_exp_f32_e32 v240, v7
	v_exp_f32_e32 v241, v8
	v_exp_f32_e32 v242, v9
	v_bfe_i32 v6, v51, 8, 1
	v_bfe_i32 v7, v51, 9, 1
	v_bfe_i32 v8, v51, 10, 1
	v_bfe_i32 v9, v51, 11, 1
	v_and_b32 v6, v6, v239
	v_and_b32 v7, v7, v240
	v_and_b32 v8, v8, v241
	v_and_b32 v9, v9, v242
	s_nop 0
	s_waitcnt lgkmcnt(2)
	v_mfma_f32_32x32x16_bf16 v[34:49], v[122:125], v[70:73], v[34:49]
	v_exp_f32_e32 v239, v10
	v_exp_f32_e32 v240, v11
	v_exp_f32_e32 v241, v12
	v_exp_f32_e32 v242, v13
	v_bfe_i32 v10, v51, 16, 1
	v_bfe_i32 v11, v51, 17, 1
	v_bfe_i32 v12, v51, 18, 1
	v_bfe_i32 v13, v51, 19, 1
	v_and_b32 v10, v10, v239
	v_and_b32 v11, v11, v240
	v_and_b32 v12, v12, v241
	v_and_b32 v13, v13, v242
	s_nop 0
	s_waitcnt lgkmcnt(0)
	v_mfma_f32_32x32x16_bf16 v[18:33], v[122:125], v[66:69], v[18:33]
	v_exp_f32_e32 v239, v14
	v_exp_f32_e32 v240, v15
	v_exp_f32_e32 v241, v16
	v_exp_f32_e32 v242, v17
	v_bfe_i32 v14, v51, 24, 1
	v_bfe_i32 v15, v51, 25, 1
	v_bfe_i32 v16, v51, 26, 1
	v_bfe_i32 v17, v51, 27, 1
	v_and_b32 v14, v14, v239
	v_and_b32 v15, v15, v240
	v_and_b32 v16, v16, v241
	v_and_b32 v17, v17, v242
	s_nop 0
	s_andn2_b64 vcc, exec, s[0:1]
	s_cbranch_vccnz .LBB0_3008
	s_waitcnt lgkmcnt(0)
	ds_read_b128 v[50:53], v231 offset:49248
	ds_read_b128 v[54:57], v231 offset:49216
	ds_read_b128 v[58:61], v231 offset:49184
	ds_read_b128 v[62:65], v231 offset:49152
	s_waitcnt lgkmcnt(3)
	v_pk_mul_f32 v[48:49], v[48:49], v[52:53]
	s_waitcnt lgkmcnt(2)
	v_pk_mul_f32 v[44:45], v[44:45], v[56:57]
	s_waitcnt lgkmcnt(1)
	v_pk_mul_f32 v[40:41], v[40:41], v[60:61]
	s_waitcnt lgkmcnt(0)
	v_pk_mul_f32 v[36:37], v[36:37], v[64:65]
	v_pk_mul_f32 v[46:47], v[46:47], v[50:51]
	v_pk_mul_f32 v[42:43], v[42:43], v[54:55]
	v_pk_mul_f32 v[38:39], v[38:39], v[58:59]
	v_pk_mul_f32 v[34:35], v[34:35], v[62:63]
	v_pk_mul_f32 v[32:33], v[32:33], v[52:53]
	v_pk_mul_f32 v[28:29], v[28:29], v[56:57]
	v_pk_mul_f32 v[24:25], v[24:25], v[60:61]
	v_pk_mul_f32 v[20:21], v[20:21], v[64:65]
	v_pk_mul_f32 v[30:31], v[30:31], v[50:51]
	v_pk_mul_f32 v[26:27], v[26:27], v[54:55]
	v_pk_mul_f32 v[22:23], v[22:23], v[58:59]
	v_pk_mul_f32 v[18:19], v[18:19], v[62:63]
